# P0 adaLN GEMV: silu(c) staging loop rewritten as 6 pipelined batches of 8 loads (was 48 serialized load-wait iterations)
# speedup vs baseline: 1.0205x; 1.0156x over previous
; DI float silu(float x) { return x * __builtin_amdgcn_rcpf(1.f + ex2(-x * LOG2E)); }
; #define PIN(i) gptr(P.in[i])
; __global__ void __launch_bounds__(512, 2) mega(Params P) {
;     ...
;             for (int idx = tid; idx < 24 * 1024; idx += 512) { const int b = idx >> 10, k = idx & 1023; const float c = b < 8 ? PIN(I_CP)[b * 1024 + k] : PIN(I_CS)[(b - 8) * 1024 + k]; sc[idx] = silu(c); }
.LBB0_16:
	s_and_saveexec_b64 s[4:5], s[0:1]
	s_cbranch_execz .LBB0_21
	v_lshlrev_b32_e32 v141, 2, v12
	v_add_u32_e32 v142, 0x1000, v141
	v_add_u32_e32 v143, 0x2000, v141
	v_add_u32_e32 v144, 0x3000, v141
	v_add_u32_e32 v145, 0x10000, v71
	s_mov_b64 s[50:51], s[60:61]
	global_load_dword v150, v141, s[50:51]
	global_load_dword v151, v141, s[50:51] offset:2048
	global_load_dword v152, v142, s[50:51]
	global_load_dword v153, v142, s[50:51] offset:2048
	global_load_dword v154, v143, s[50:51]
	global_load_dword v155, v143, s[50:51] offset:2048
	global_load_dword v156, v144, s[50:51]
	global_load_dword v157, v144, s[50:51] offset:2048
	s_add_u32 s50, s50, 0x4000
	s_addc_u32 s51, s51, 0
	global_load_dword v160, v141, s[50:51]
	global_load_dword v161, v141, s[50:51] offset:2048
	global_load_dword v162, v142, s[50:51]
	global_load_dword v163, v142, s[50:51] offset:2048
	global_load_dword v164, v143, s[50:51]
	global_load_dword v165, v143, s[50:51] offset:2048
	global_load_dword v166, v144, s[50:51]
	global_load_dword v167, v144, s[50:51] offset:2048
	s_add_u32 s50, s50, 0x4000
	s_addc_u32 s51, s51, 0
	s_waitcnt vmcnt(8)
	v_mul_f32_e32 v170, 0xbfb8aa3b, v150
	v_mul_f32_e32 v171, 0xbfb8aa3b, v151
	v_mul_f32_e32 v172, 0xbfb8aa3b, v152
	v_mul_f32_e32 v173, 0xbfb8aa3b, v153
	v_mul_f32_e32 v174, 0xbfb8aa3b, v154
	v_mul_f32_e32 v175, 0xbfb8aa3b, v155
	v_mul_f32_e32 v176, 0xbfb8aa3b, v156
	v_mul_f32_e32 v177, 0xbfb8aa3b, v157
	v_exp_f32_e32 v170, v170
	v_exp_f32_e32 v171, v171
	v_exp_f32_e32 v172, v172
	v_exp_f32_e32 v173, v173
	v_exp_f32_e32 v174, v174
	v_exp_f32_e32 v175, v175
	v_exp_f32_e32 v176, v176
	v_exp_f32_e32 v177, v177
	v_add_f32_e32 v170, 1.0, v170
	v_add_f32_e32 v171, 1.0, v171
	v_add_f32_e32 v172, 1.0, v172
	v_add_f32_e32 v173, 1.0, v173
	v_add_f32_e32 v174, 1.0, v174
	v_add_f32_e32 v175, 1.0, v175
	v_add_f32_e32 v176, 1.0, v176
	v_add_f32_e32 v177, 1.0, v177
	v_rcp_f32_e32 v170, v170
	v_rcp_f32_e32 v171, v171
	v_rcp_f32_e32 v172, v172
	v_rcp_f32_e32 v173, v173
	v_rcp_f32_e32 v174, v174
	v_rcp_f32_e32 v175, v175
	v_rcp_f32_e32 v176, v176
	v_rcp_f32_e32 v177, v177
	v_mul_f32_e32 v170, v150, v170
	v_mul_f32_e32 v171, v151, v171
	v_mul_f32_e32 v172, v152, v172
	v_mul_f32_e32 v173, v153, v173
	v_mul_f32_e32 v174, v154, v174
	v_mul_f32_e32 v175, v155, v175
	v_mul_f32_e32 v176, v156, v176
	v_mul_f32_e32 v177, v157, v177
	ds_write_b32 v71, v170
	ds_write_b32 v71, v171 offset:2048
	ds_write_b32 v71, v172 offset:4096
	ds_write_b32 v71, v173 offset:6144
	ds_write_b32 v71, v174 offset:8192
	ds_write_b32 v71, v175 offset:10240
	ds_write_b32 v71, v176 offset:12288
	ds_write_b32 v71, v177 offset:14336
	s_mov_b64 s[50:51], s[62:63]
	global_load_dword v150, v141, s[50:51]
	global_load_dword v151, v141, s[50:51] offset:2048
	global_load_dword v152, v142, s[50:51]
	global_load_dword v153, v142, s[50:51] offset:2048
	global_load_dword v154, v143, s[50:51]
	global_load_dword v155, v143, s[50:51] offset:2048
	global_load_dword v156, v144, s[50:51]
	global_load_dword v157, v144, s[50:51] offset:2048
	s_add_u32 s50, s50, 0x4000
	s_addc_u32 s51, s51, 0
	s_waitcnt vmcnt(8)
	v_mul_f32_e32 v180, 0xbfb8aa3b, v160
	v_mul_f32_e32 v181, 0xbfb8aa3b, v161
	v_mul_f32_e32 v182, 0xbfb8aa3b, v162
	v_mul_f32_e32 v183, 0xbfb8aa3b, v163
	v_mul_f32_e32 v184, 0xbfb8aa3b, v164
	v_mul_f32_e32 v185, 0xbfb8aa3b, v165
	v_mul_f32_e32 v186, 0xbfb8aa3b, v166
	v_mul_f32_e32 v187, 0xbfb8aa3b, v167
	v_exp_f32_e32 v180, v180
	v_exp_f32_e32 v181, v181
	v_exp_f32_e32 v182, v182
	v_exp_f32_e32 v183, v183
	v_exp_f32_e32 v184, v184
	v_exp_f32_e32 v185, v185
	v_exp_f32_e32 v186, v186
	v_exp_f32_e32 v187, v187
	v_add_f32_e32 v180, 1.0, v180
	v_add_f32_e32 v181, 1.0, v181
	v_add_f32_e32 v182, 1.0, v182
	v_add_f32_e32 v183, 1.0, v183
	v_add_f32_e32 v184, 1.0, v184
	v_add_f32_e32 v185, 1.0, v185
	v_add_f32_e32 v186, 1.0, v186
	v_add_f32_e32 v187, 1.0, v187
	v_rcp_f32_e32 v180, v180
	v_rcp_f32_e32 v181, v181
	v_rcp_f32_e32 v182, v182
	v_rcp_f32_e32 v183, v183
	v_rcp_f32_e32 v184, v184
	v_rcp_f32_e32 v185, v185
	v_rcp_f32_e32 v186, v186
	v_rcp_f32_e32 v187, v187
	v_mul_f32_e32 v180, v160, v180
	v_mul_f32_e32 v181, v161, v181
	v_mul_f32_e32 v182, v162, v182
	v_mul_f32_e32 v183, v163, v183
	v_mul_f32_e32 v184, v164, v184
	v_mul_f32_e32 v185, v165, v185
	v_mul_f32_e32 v186, v166, v186
	v_mul_f32_e32 v187, v167, v187
	ds_write_b32 v71, v180 offset:16384
	ds_write_b32 v71, v181 offset:18432
	ds_write_b32 v71, v182 offset:20480
	ds_write_b32 v71, v183 offset:22528
	ds_write_b32 v71, v184 offset:24576
	ds_write_b32 v71, v185 offset:26624
	ds_write_b32 v71, v186 offset:28672
	ds_write_b32 v71, v187 offset:30720
	global_load_dword v160, v141, s[50:51]
	global_load_dword v161, v141, s[50:51] offset:2048
	global_load_dword v162, v142, s[50:51]
	global_load_dword v163, v142, s[50:51] offset:2048
	global_load_dword v164, v143, s[50:51]
	global_load_dword v165, v143, s[50:51] offset:2048
	global_load_dword v166, v144, s[50:51]
	global_load_dword v167, v144, s[50:51] offset:2048
	s_add_u32 s50, s50, 0x4000
	s_addc_u32 s51, s51, 0
	s_waitcnt vmcnt(8)
; DI float silu(float x) { return x * __builtin_amdgcn_rcpf(1.f + ex2(-x * LOG2E)); }
; #define PIN(i) gptr(P.in[i])
; __global__ void __launch_bounds__(512, 2) mega(Params P) {
;     ...
;             for (int idx = tid; idx < 24 * 1024; idx += 512) { const int b = idx >> 10, k = idx & 1023; const float c = b < 8 ? PIN(I_CP)[b * 1024 + k] : PIN(I_CS)[(b - 8) * 1024 + k]; sc[idx] = silu(c); }
	v_mul_f32_e32 v170, 0xbfb8aa3b, v150
	v_mul_f32_e32 v171, 0xbfb8aa3b, v151
	v_mul_f32_e32 v172, 0xbfb8aa3b, v152
	v_mul_f32_e32 v173, 0xbfb8aa3b, v153
	v_mul_f32_e32 v174, 0xbfb8aa3b, v154
	v_mul_f32_e32 v175, 0xbfb8aa3b, v155
	v_mul_f32_e32 v176, 0xbfb8aa3b, v156
	v_mul_f32_e32 v177, 0xbfb8aa3b, v157
	v_exp_f32_e32 v170, v170
	v_exp_f32_e32 v171, v171
	v_exp_f32_e32 v172, v172
	v_exp_f32_e32 v173, v173
	v_exp_f32_e32 v174, v174
	v_exp_f32_e32 v175, v175
	v_exp_f32_e32 v176, v176
	v_exp_f32_e32 v177, v177
	v_add_f32_e32 v170, 1.0, v170
	v_add_f32_e32 v171, 1.0, v171
	v_add_f32_e32 v172, 1.0, v172
	v_add_f32_e32 v173, 1.0, v173
	v_add_f32_e32 v174, 1.0, v174
	v_add_f32_e32 v175, 1.0, v175
	v_add_f32_e32 v176, 1.0, v176
	v_add_f32_e32 v177, 1.0, v177
	v_rcp_f32_e32 v170, v170
	v_rcp_f32_e32 v171, v171
	v_rcp_f32_e32 v172, v172
	v_rcp_f32_e32 v173, v173
	v_rcp_f32_e32 v174, v174
	v_rcp_f32_e32 v175, v175
	v_rcp_f32_e32 v176, v176
	v_rcp_f32_e32 v177, v177
	v_mul_f32_e32 v170, v150, v170
	v_mul_f32_e32 v171, v151, v171
	v_mul_f32_e32 v172, v152, v172
	v_mul_f32_e32 v173, v153, v173
	v_mul_f32_e32 v174, v154, v174
	v_mul_f32_e32 v175, v155, v175
	v_mul_f32_e32 v176, v156, v176
	v_mul_f32_e32 v177, v157, v177
	ds_write_b32 v71, v170 offset:32768
	ds_write_b32 v71, v171 offset:34816
	ds_write_b32 v71, v172 offset:36864
	ds_write_b32 v71, v173 offset:38912
	ds_write_b32 v71, v174 offset:40960
	ds_write_b32 v71, v175 offset:43008
	ds_write_b32 v71, v176 offset:45056
	ds_write_b32 v71, v177 offset:47104
	global_load_dword v150, v141, s[50:51]
	global_load_dword v151, v141, s[50:51] offset:2048
	global_load_dword v152, v142, s[50:51]
	global_load_dword v153, v142, s[50:51] offset:2048
	global_load_dword v154, v143, s[50:51]
	global_load_dword v155, v143, s[50:51] offset:2048
	global_load_dword v156, v144, s[50:51]
	global_load_dword v157, v144, s[50:51] offset:2048
	s_add_u32 s50, s50, 0x4000
	s_addc_u32 s51, s51, 0
	s_waitcnt vmcnt(8)
	v_mul_f32_e32 v180, 0xbfb8aa3b, v160
	v_mul_f32_e32 v181, 0xbfb8aa3b, v161
	v_mul_f32_e32 v182, 0xbfb8aa3b, v162
	v_mul_f32_e32 v183, 0xbfb8aa3b, v163
	v_mul_f32_e32 v184, 0xbfb8aa3b, v164
	v_mul_f32_e32 v185, 0xbfb8aa3b, v165
	v_mul_f32_e32 v186, 0xbfb8aa3b, v166
	v_mul_f32_e32 v187, 0xbfb8aa3b, v167
	v_exp_f32_e32 v180, v180
	v_exp_f32_e32 v181, v181
	v_exp_f32_e32 v182, v182
	v_exp_f32_e32 v183, v183
	v_exp_f32_e32 v184, v184
	v_exp_f32_e32 v185, v185
	v_exp_f32_e32 v186, v186
	v_exp_f32_e32 v187, v187
	v_add_f32_e32 v180, 1.0, v180
	v_add_f32_e32 v181, 1.0, v181
	v_add_f32_e32 v182, 1.0, v182
	v_add_f32_e32 v183, 1.0, v183
	v_add_f32_e32 v184, 1.0, v184
	v_add_f32_e32 v185, 1.0, v185
	v_add_f32_e32 v186, 1.0, v186
	v_add_f32_e32 v187, 1.0, v187
	v_rcp_f32_e32 v180, v180
	v_rcp_f32_e32 v181, v181
	v_rcp_f32_e32 v182, v182
	v_rcp_f32_e32 v183, v183
	v_rcp_f32_e32 v184, v184
	v_rcp_f32_e32 v185, v185
	v_rcp_f32_e32 v186, v186
	v_rcp_f32_e32 v187, v187
	v_mul_f32_e32 v180, v160, v180
	v_mul_f32_e32 v181, v161, v181
	v_mul_f32_e32 v182, v162, v182
	v_mul_f32_e32 v183, v163, v183
	v_mul_f32_e32 v184, v164, v184
	v_mul_f32_e32 v185, v165, v185
	v_mul_f32_e32 v186, v166, v186
	v_mul_f32_e32 v187, v167, v187
	ds_write_b32 v71, v180 offset:49152
	ds_write_b32 v71, v181 offset:51200
	ds_write_b32 v71, v182 offset:53248
	ds_write_b32 v71, v183 offset:55296
	ds_write_b32 v71, v184 offset:57344
	ds_write_b32 v71, v185 offset:59392
	ds_write_b32 v71, v186 offset:61440
	ds_write_b32 v71, v187 offset:63488
	global_load_dword v160, v141, s[50:51]
	global_load_dword v161, v141, s[50:51] offset:2048
	global_load_dword v162, v142, s[50:51]
	global_load_dword v163, v142, s[50:51] offset:2048
	global_load_dword v164, v143, s[50:51]
	global_load_dword v165, v143, s[50:51] offset:2048
	global_load_dword v166, v144, s[50:51]
	global_load_dword v167, v144, s[50:51] offset:2048
	s_add_u32 s50, s50, 0x4000
	s_addc_u32 s51, s51, 0
	s_waitcnt vmcnt(8)
	v_mul_f32_e32 v170, 0xbfb8aa3b, v150
	v_mul_f32_e32 v171, 0xbfb8aa3b, v151
	v_mul_f32_e32 v172, 0xbfb8aa3b, v152
	v_mul_f32_e32 v173, 0xbfb8aa3b, v153
	v_mul_f32_e32 v174, 0xbfb8aa3b, v154
	v_mul_f32_e32 v175, 0xbfb8aa3b, v155
	v_mul_f32_e32 v176, 0xbfb8aa3b, v156
	v_mul_f32_e32 v177, 0xbfb8aa3b, v157
	v_exp_f32_e32 v170, v170
	v_exp_f32_e32 v171, v171
	v_exp_f32_e32 v172, v172
	v_exp_f32_e32 v173, v173
	v_exp_f32_e32 v174, v174
	v_exp_f32_e32 v175, v175
	v_exp_f32_e32 v176, v176
	v_exp_f32_e32 v177, v177
	v_add_f32_e32 v170, 1.0, v170
	v_add_f32_e32 v171, 1.0, v171
	v_add_f32_e32 v172, 1.0, v172
	v_add_f32_e32 v173, 1.0, v173
	v_add_f32_e32 v174, 1.0, v174
	v_add_f32_e32 v175, 1.0, v175
	v_add_f32_e32 v176, 1.0, v176
	v_add_f32_e32 v177, 1.0, v177
	v_rcp_f32_e32 v170, v170
	v_rcp_f32_e32 v171, v171
	v_rcp_f32_e32 v172, v172
	v_rcp_f32_e32 v173, v173
	v_rcp_f32_e32 v174, v174
	v_rcp_f32_e32 v175, v175
	v_rcp_f32_e32 v176, v176
	v_rcp_f32_e32 v177, v177
	v_mul_f32_e32 v170, v150, v170
	v_mul_f32_e32 v171, v151, v171
	v_mul_f32_e32 v172, v152, v172
	v_mul_f32_e32 v173, v153, v173
	v_mul_f32_e32 v174, v154, v174
	v_mul_f32_e32 v175, v155, v175
	v_mul_f32_e32 v176, v156, v176
	v_mul_f32_e32 v177, v157, v177
	ds_write_b32 v145, v170
	ds_write_b32 v145, v171 offset:2048
	ds_write_b32 v145, v172 offset:4096
	ds_write_b32 v145, v173 offset:6144
	ds_write_b32 v145, v174 offset:8192
	ds_write_b32 v145, v175 offset:10240
	ds_write_b32 v145, v176 offset:12288
	ds_write_b32 v145, v177 offset:14336
	s_waitcnt vmcnt(0)
	v_mul_f32_e32 v180, 0xbfb8aa3b, v160
	v_mul_f32_e32 v181, 0xbfb8aa3b, v161
	v_mul_f32_e32 v182, 0xbfb8aa3b, v162
	v_mul_f32_e32 v183, 0xbfb8aa3b, v163
	v_mul_f32_e32 v184, 0xbfb8aa3b, v164
	v_mul_f32_e32 v185, 0xbfb8aa3b, v165
	v_mul_f32_e32 v186, 0xbfb8aa3b, v166
	v_mul_f32_e32 v187, 0xbfb8aa3b, v167
	v_exp_f32_e32 v180, v180
	v_exp_f32_e32 v181, v181
	v_exp_f32_e32 v182, v182
	v_exp_f32_e32 v183, v183
	v_exp_f32_e32 v184, v184
	v_exp_f32_e32 v185, v185
	v_exp_f32_e32 v186, v186
	v_exp_f32_e32 v187, v187
	v_add_f32_e32 v180, 1.0, v180
	v_add_f32_e32 v181, 1.0, v181
	v_add_f32_e32 v182, 1.0, v182
	v_add_f32_e32 v183, 1.0, v183
	v_add_f32_e32 v184, 1.0, v184
	v_add_f32_e32 v185, 1.0, v185
	v_add_f32_e32 v186, 1.0, v186
	v_add_f32_e32 v187, 1.0, v187
	v_rcp_f32_e32 v180, v180
	v_rcp_f32_e32 v181, v181
	v_rcp_f32_e32 v182, v182
	v_rcp_f32_e32 v183, v183
	v_rcp_f32_e32 v184, v184
	v_rcp_f32_e32 v185, v185
	v_rcp_f32_e32 v186, v186
	v_rcp_f32_e32 v187, v187
	v_mul_f32_e32 v180, v160, v180
	v_mul_f32_e32 v181, v161, v181
	v_mul_f32_e32 v182, v162, v182
	v_mul_f32_e32 v183, v163, v183
	v_mul_f32_e32 v184, v164, v184
	v_mul_f32_e32 v185, v165, v185
	v_mul_f32_e32 v186, v166, v186
	v_mul_f32_e32 v187, v167, v187
	ds_write_b32 v145, v180 offset:16384
	ds_write_b32 v145, v181 offset:18432
	ds_write_b32 v145, v182 offset:20480
	ds_write_b32 v145, v183 offset:22528
	ds_write_b32 v145, v184 offset:24576
	ds_write_b32 v145, v185 offset:26624
	ds_write_b32 v145, v186 offset:28672
	ds_write_b32 v145, v187 offset:30720
